# o30 + prologue x->bf16 row conversion de-serialised: 8 loads of a row in flight together instead of 8 load-wait-store round trips
# speedup vs baseline: 1.0046x; 1.0046x over previous
.LBB0_117:
	s_or_b64 exec, exec, s[6:7]
	v_lshl_add_u64 v[16:17], v[12:13], 0, v[8:9]
	v_add_co_u32_e32 v14, vcc, s9, v16
	global_load_dwordx4 v[204:207], v[16:17], off
	global_load_dwordx4 v[208:211], v[16:17], off offset:1024
	v_addc_co_u32_e32 v15, vcc, 0, v17, vcc
	global_load_dwordx4 v[212:215], v[16:17], off offset:2048
	global_load_dwordx4 v[216:219], v[16:17], off offset:3072
	global_load_dwordx4 v[220:223], v[14:15], off
	global_load_dwordx4 v[224:227], v[14:15], off offset:1024
	global_load_dwordx4 v[228:231], v[14:15], off offset:2048
	global_load_dwordx4 v[232:235], v[14:15], off offset:3072
	v_lshlrev_b64 v[10:11], 12, v[10:11]
	v_lshl_add_u64 v[18:19], v[4:5], 0, v[10:11]
	v_lshl_add_u64 v[130:131], v[130:131], 0, s[42:43]
	v_lshl_add_u64 v[6:7], v[6:7], 0, s[2:3]
	v_cmp_lt_i32_e32 vcc, s10, v130
	s_or_b64 s[4:5], vcc, s[4:5]
	s_waitcnt vmcnt(7)
	v_cvt_pk_bf16_f32 v236, v204, v205
	v_cvt_pk_bf16_f32 v237, v206, v207
	s_waitcnt vmcnt(6)
	v_cvt_pk_bf16_f32 v238, v208, v209
	v_cvt_pk_bf16_f32 v239, v210, v211
	s_waitcnt vmcnt(5)
	v_cvt_pk_bf16_f32 v240, v212, v213
	v_cvt_pk_bf16_f32 v241, v214, v215
	s_waitcnt vmcnt(4)
	v_cvt_pk_bf16_f32 v242, v216, v217
	v_cvt_pk_bf16_f32 v243, v218, v219
	s_waitcnt vmcnt(3)
	v_cvt_pk_bf16_f32 v244, v220, v221
	v_cvt_pk_bf16_f32 v245, v222, v223
	s_waitcnt vmcnt(2)
	v_cvt_pk_bf16_f32 v246, v224, v225
	v_cvt_pk_bf16_f32 v247, v226, v227
	s_waitcnt vmcnt(1)
	v_cvt_pk_bf16_f32 v248, v228, v229
	v_cvt_pk_bf16_f32 v249, v230, v231
	s_waitcnt vmcnt(0)
	v_cvt_pk_bf16_f32 v250, v232, v233
	v_cvt_pk_bf16_f32 v251, v234, v235
	global_store_dwordx2 v[18:19], v[236:237], off
	global_store_dwordx2 v[18:19], v[238:239], off offset:512
	global_store_dwordx2 v[18:19], v[240:241], off offset:1024
	global_store_dwordx2 v[18:19], v[242:243], off offset:1536
	global_store_dwordx2 v[18:19], v[244:245], off offset:2048
	global_store_dwordx2 v[18:19], v[246:247], off offset:2560
	global_store_dwordx2 v[18:19], v[248:249], off offset:3072
	global_store_dwordx2 v[18:19], v[250:251], off offset:3584
	s_andn2_b64 exec, exec, s[4:5]
	s_cbranch_execz .LBB0_120
